# sample-row tail row reduction uses DPP adds + permlane swaps instead of six serial ds_bpermute round trips (bit-identical)
# baseline (speedup 1.0000x reference)
.Lsr_skip:
	s_mov_b64 exec, s[98:99]
	global_load_dwordx4 v[136:139], v[0:1], off
	global_load_dwordx4 v[140:143], v[0:1], off offset:16
	global_load_dwordx4 v[192:195], v[0:1], off offset:32
	global_load_dwordx4 v[196:199], v[0:1], off offset:48
	v_lshl_add_u64 v[0:1], s[90:91], 0, v[144:145]
	global_load_dwordx4 v[12:15], v[0:1], off
	global_load_dwordx4 v[8:11], v[0:1], off offset:64
	global_load_dwordx4 v[4:7], v[0:1], off offset:512
	s_nop 0
	global_load_dwordx4 v[0:3], v[0:1], off offset:576
	v_mov_b32_e32 v134, 0x358637bd
	s_mov_b32 s2, 0x800000
	s_waitcnt vmcnt(6)
	v_pk_add_f32 v[138:139], v[138:139], v[142:143]
	v_pk_add_f32 v[136:137], v[136:137], v[140:141]
	s_waitcnt vmcnt(4)
	v_pk_add_f32 v[140:141], v[194:195], v[198:199]
	v_pk_add_f32 v[142:143], v[192:193], v[196:197]
	v_pk_add_f32 v[138:139], v[138:139], v[140:141]
	v_pk_add_f32 v[136:137], v[136:137], v[142:143]
	s_nop 0
	v_pk_mov_b32 v[140:141], v[136:137], v[138:139] op_sel:[1,0]
	v_mov_b32_e32 v137, v139
	v_pk_add_f32 v[136:137], v[140:141], v[136:137]
	v_lshl_add_u64 v[138:139], s[0:1], 0, v[176:177]
	v_add_f32_e32 v135, v136, v137
	v_fmamk_f32 v135, v135, 0x3a800000, v134
	v_mul_f32_e32 v136, 0x4b800000, v135
	v_cmp_gt_f32_e32 vcc, s2, v135
	s_nop 1
	v_cndmask_b32_e32 v135, v135, v136, vcc
	v_rsq_f32_e32 v135, v135
	v_lshl_add_u64 v[136:137], s[76:77], 0, v[146:147]
	v_lshl_add_u64 v[136:137], v[136:137], 0, v[144:145]
	v_mul_f32_e32 v140, 0x45800000, v135
	v_cndmask_b32_e32 v140, v135, v140, vcc
	v_pk_mul_f32 v[124:125], v[124:125], v[140:141] op_sel_hi:[1,0]
	v_pk_mul_f32 v[126:127], v[126:127], v[140:141] op_sel_hi:[1,0]
	v_pk_mul_f32 v[120:121], v[120:121], v[140:141] op_sel_hi:[1,0]
	v_pk_mul_f32 v[122:123], v[122:123], v[140:141] op_sel_hi:[1,0]
	v_pk_mul_f32 v[142:143], v[116:117], v[140:141] op_sel_hi:[1,0]
	v_pk_mul_f32 v[146:147], v[118:119], v[140:141] op_sel_hi:[1,0]
	v_pk_mul_f32 v[174:175], v[112:113], v[140:141] op_sel_hi:[1,0]
	v_pk_mul_f32 v[140:141], v[114:115], v[140:141] op_sel_hi:[1,0]
	s_waitcnt vmcnt(3)
	v_pk_mul_f32 v[114:115], v[14:15], v[126:127]
	v_pk_mul_f32 v[112:113], v[12:13], v[124:125]
	s_waitcnt vmcnt(2)
	v_pk_mul_f32 v[118:119], v[10:11], v[122:123]
	v_pk_mul_f32 v[116:117], v[8:9], v[120:121]
	s_waitcnt vmcnt(1)
	v_pk_mul_f32 v[122:123], v[6:7], v[146:147]
	v_pk_mul_f32 v[120:121], v[4:5], v[142:143]
	s_waitcnt vmcnt(0)
	v_pk_mul_f32 v[126:127], v[2:3], v[140:141]
	v_pk_mul_f32 v[124:125], v[0:1], v[174:175]
	global_store_dwordx4 v[136:137], v[112:115], off
	global_store_dwordx4 v[136:137], v[116:119], off offset:64
	global_store_dwordx4 v[136:137], v[120:123], off offset:512
	global_store_dwordx4 v[136:137], v[124:127], off offset:576
	global_load_dwordx4 v[112:115], v[138:139], off
	s_nop 0
	global_load_dwordx4 v[116:119], v[138:139], off offset:16
	global_load_dwordx4 v[120:123], v[138:139], off offset:32
	global_load_dwordx4 v[124:127], v[138:139], off offset:48
	s_waitcnt vmcnt(2)
	v_pk_add_f32 v[114:115], v[114:115], v[118:119]
	v_pk_add_f32 v[112:113], v[112:113], v[116:117]
	s_waitcnt vmcnt(0)
	v_pk_add_f32 v[116:117], v[122:123], v[126:127]
	v_pk_add_f32 v[118:119], v[120:121], v[124:125]
	v_pk_add_f32 v[114:115], v[114:115], v[116:117]
	v_pk_add_f32 v[112:113], v[112:113], v[118:119]
	s_nop 0
	v_pk_mov_b32 v[116:117], v[112:113], v[114:115] op_sel:[1,0]
	v_mov_b32_e32 v113, v115
	v_pk_add_f32 v[112:113], v[116:117], v[112:113]
	v_lshl_add_u64 v[114:115], s[0:1], 0, v[178:179]
	v_add_f32_e32 v112, v112, v113
	v_fmamk_f32 v112, v112, 0x3a800000, v134
	v_mul_f32_e32 v113, 0x4b800000, v112
	v_cmp_gt_f32_e32 vcc, s2, v112
	s_nop 1
	v_cndmask_b32_e32 v112, v112, v113, vcc
	v_rsq_f32_e32 v116, v112
	v_lshl_add_u64 v[112:113], s[76:77], 0, v[148:149]
	v_lshl_add_u64 v[112:113], v[112:113], 0, v[144:145]
	v_mul_f32_e32 v117, 0x45800000, v116
	v_cndmask_b32_e32 v116, v116, v117, vcc
	v_pk_mul_f32 v[108:109], v[108:109], v[116:117] op_sel_hi:[1,0]
	v_pk_mul_f32 v[110:111], v[110:111], v[116:117] op_sel_hi:[1,0]
	v_pk_mul_f32 v[104:105], v[104:105], v[116:117] op_sel_hi:[1,0]
	v_pk_mul_f32 v[106:107], v[106:107], v[116:117] op_sel_hi:[1,0]
	v_pk_mul_f32 v[118:119], v[100:101], v[116:117] op_sel_hi:[1,0]
	v_pk_mul_f32 v[120:121], v[102:103], v[116:117] op_sel_hi:[1,0]
	v_pk_mul_f32 v[122:123], v[96:97], v[116:117] op_sel_hi:[1,0]
	v_pk_mul_f32 v[116:117], v[98:99], v[116:117] op_sel_hi:[1,0]
	v_pk_mul_f32 v[98:99], v[14:15], v[110:111]
	v_pk_mul_f32 v[96:97], v[12:13], v[108:109]
	v_pk_mul_f32 v[102:103], v[10:11], v[106:107]
	v_pk_mul_f32 v[100:101], v[8:9], v[104:105]
	v_pk_mul_f32 v[106:107], v[6:7], v[120:121]
	v_pk_mul_f32 v[104:105], v[4:5], v[118:119]
	v_pk_mul_f32 v[110:111], v[2:3], v[116:117]
	v_pk_mul_f32 v[108:109], v[0:1], v[122:123]
	global_store_dwordx4 v[112:113], v[96:99], off
	global_store_dwordx4 v[112:113], v[100:103], off offset:64
	global_store_dwordx4 v[112:113], v[104:107], off offset:512
	global_store_dwordx4 v[112:113], v[108:111], off offset:576
	global_load_dwordx4 v[96:99], v[114:115], off
	s_nop 0
	global_load_dwordx4 v[100:103], v[114:115], off offset:16
	global_load_dwordx4 v[104:107], v[114:115], off offset:32
	global_load_dwordx4 v[108:111], v[114:115], off offset:48
	s_waitcnt vmcnt(2)
	v_pk_add_f32 v[98:99], v[98:99], v[102:103]
	v_pk_add_f32 v[96:97], v[96:97], v[100:101]
	s_waitcnt vmcnt(0)
	v_pk_add_f32 v[100:101], v[106:107], v[110:111]
	v_pk_add_f32 v[102:103], v[104:105], v[108:109]
	v_pk_add_f32 v[98:99], v[98:99], v[100:101]
	v_pk_add_f32 v[96:97], v[96:97], v[102:103]
	s_nop 0
	v_pk_mov_b32 v[100:101], v[96:97], v[98:99] op_sel:[1,0]
	v_mov_b32_e32 v97, v99
	v_pk_add_f32 v[96:97], v[100:101], v[96:97]
	v_lshl_add_u64 v[98:99], s[0:1], 0, v[180:181]
	v_add_f32_e32 v96, v96, v97
	v_fmamk_f32 v96, v96, 0x3a800000, v134
	v_mul_f32_e32 v97, 0x4b800000, v96
	v_cmp_gt_f32_e32 vcc, s2, v96
	s_nop 1
	v_cndmask_b32_e32 v96, v96, v97, vcc
	v_rsq_f32_e32 v100, v96
	v_lshl_add_u64 v[96:97], s[76:77], 0, v[150:151]
	v_lshl_add_u64 v[96:97], v[96:97], 0, v[144:145]
	v_mul_f32_e32 v101, 0x45800000, v100
	v_cndmask_b32_e32 v100, v100, v101, vcc
	v_pk_mul_f32 v[92:93], v[92:93], v[100:101] op_sel_hi:[1,0]
	v_pk_mul_f32 v[94:95], v[94:95], v[100:101] op_sel_hi:[1,0]
	v_pk_mul_f32 v[88:89], v[88:89], v[100:101] op_sel_hi:[1,0]
	v_pk_mul_f32 v[90:91], v[90:91], v[100:101] op_sel_hi:[1,0]
	v_pk_mul_f32 v[102:103], v[84:85], v[100:101] op_sel_hi:[1,0]
	v_pk_mul_f32 v[104:105], v[86:87], v[100:101] op_sel_hi:[1,0]
	v_pk_mul_f32 v[106:107], v[80:81], v[100:101] op_sel_hi:[1,0]
	v_pk_mul_f32 v[100:101], v[82:83], v[100:101] op_sel_hi:[1,0]
	v_pk_mul_f32 v[82:83], v[14:15], v[94:95]
	v_pk_mul_f32 v[80:81], v[12:13], v[92:93]
	v_pk_mul_f32 v[86:87], v[10:11], v[90:91]
	v_pk_mul_f32 v[84:85], v[8:9], v[88:89]
	v_pk_mul_f32 v[90:91], v[6:7], v[104:105]
	v_pk_mul_f32 v[88:89], v[4:5], v[102:103]
	v_pk_mul_f32 v[94:95], v[2:3], v[100:101]
	v_pk_mul_f32 v[92:93], v[0:1], v[106:107]
	global_store_dwordx4 v[96:97], v[80:83], off
	global_store_dwordx4 v[96:97], v[84:87], off offset:64
	global_store_dwordx4 v[96:97], v[88:91], off offset:512
	global_store_dwordx4 v[96:97], v[92:95], off offset:576
	global_load_dwordx4 v[80:83], v[98:99], off
	s_nop 0
	global_load_dwordx4 v[84:87], v[98:99], off offset:16
	global_load_dwordx4 v[88:91], v[98:99], off offset:32
	global_load_dwordx4 v[92:95], v[98:99], off offset:48
	s_waitcnt vmcnt(2)
	v_pk_add_f32 v[82:83], v[82:83], v[86:87]
	v_pk_add_f32 v[80:81], v[80:81], v[84:85]
	s_waitcnt vmcnt(0)
	v_pk_add_f32 v[84:85], v[90:91], v[94:95]
	v_pk_add_f32 v[86:87], v[88:89], v[92:93]
	v_pk_add_f32 v[82:83], v[82:83], v[84:85]
	v_pk_add_f32 v[80:81], v[80:81], v[86:87]
	s_nop 0
	v_pk_mov_b32 v[84:85], v[80:81], v[82:83] op_sel:[1,0]
	v_mov_b32_e32 v81, v83
	v_pk_add_f32 v[80:81], v[84:85], v[80:81]
	v_lshl_add_u64 v[82:83], s[0:1], 0, v[182:183]
	v_add_f32_e32 v80, v80, v81
	v_fmamk_f32 v80, v80, 0x3a800000, v134
	v_mul_f32_e32 v81, 0x4b800000, v80
	v_cmp_gt_f32_e32 vcc, s2, v80
	s_nop 1
	v_cndmask_b32_e32 v80, v80, v81, vcc
	v_rsq_f32_e32 v84, v80
	v_lshl_add_u64 v[80:81], s[76:77], 0, v[152:153]
	v_lshl_add_u64 v[80:81], v[80:81], 0, v[144:145]
	v_mul_f32_e32 v85, 0x45800000, v84
	v_cndmask_b32_e32 v84, v84, v85, vcc
	v_pk_mul_f32 v[76:77], v[76:77], v[84:85] op_sel_hi:[1,0]
	v_pk_mul_f32 v[78:79], v[78:79], v[84:85] op_sel_hi:[1,0]
	v_pk_mul_f32 v[72:73], v[72:73], v[84:85] op_sel_hi:[1,0]
	v_pk_mul_f32 v[74:75], v[74:75], v[84:85] op_sel_hi:[1,0]
	v_pk_mul_f32 v[86:87], v[68:69], v[84:85] op_sel_hi:[1,0]
	v_pk_mul_f32 v[88:89], v[70:71], v[84:85] op_sel_hi:[1,0]
	v_pk_mul_f32 v[90:91], v[64:65], v[84:85] op_sel_hi:[1,0]
	v_pk_mul_f32 v[84:85], v[66:67], v[84:85] op_sel_hi:[1,0]
	v_pk_mul_f32 v[66:67], v[14:15], v[78:79]
	v_pk_mul_f32 v[64:65], v[12:13], v[76:77]
	v_pk_mul_f32 v[70:71], v[10:11], v[74:75]
	v_pk_mul_f32 v[68:69], v[8:9], v[72:73]
	v_pk_mul_f32 v[74:75], v[6:7], v[88:89]
	v_pk_mul_f32 v[72:73], v[4:5], v[86:87]
	v_pk_mul_f32 v[78:79], v[2:3], v[84:85]
	v_pk_mul_f32 v[76:77], v[0:1], v[90:91]
	global_store_dwordx4 v[80:81], v[64:67], off
	global_store_dwordx4 v[80:81], v[68:71], off offset:64
	global_store_dwordx4 v[80:81], v[72:75], off offset:512
	global_store_dwordx4 v[80:81], v[76:79], off offset:576
	global_load_dwordx4 v[64:67], v[82:83], off
	s_nop 0
	global_load_dwordx4 v[68:71], v[82:83], off offset:16
	global_load_dwordx4 v[72:75], v[82:83], off offset:32
	global_load_dwordx4 v[76:79], v[82:83], off offset:48
	s_waitcnt vmcnt(2)
	v_pk_add_f32 v[66:67], v[66:67], v[70:71]
	v_pk_add_f32 v[64:65], v[64:65], v[68:69]
	s_waitcnt vmcnt(0)
	v_pk_add_f32 v[68:69], v[74:75], v[78:79]
	v_pk_add_f32 v[70:71], v[72:73], v[76:77]
	v_pk_add_f32 v[66:67], v[66:67], v[68:69]
	v_pk_add_f32 v[64:65], v[64:65], v[70:71]
	s_nop 0
	v_pk_mov_b32 v[68:69], v[64:65], v[66:67] op_sel:[1,0]
	v_mov_b32_e32 v65, v67
	v_pk_add_f32 v[64:65], v[68:69], v[64:65]
	v_lshl_add_u64 v[66:67], s[0:1], 0, v[184:185]
	v_add_f32_e32 v64, v64, v65
	v_fmamk_f32 v64, v64, 0x3a800000, v134
	v_mul_f32_e32 v65, 0x4b800000, v64
	v_cmp_gt_f32_e32 vcc, s2, v64
	s_nop 1
	v_cndmask_b32_e32 v64, v64, v65, vcc
	v_rsq_f32_e32 v68, v64
	v_lshl_add_u64 v[64:65], s[76:77], 0, v[154:155]
	v_lshl_add_u64 v[64:65], v[64:65], 0, v[144:145]
	v_mul_f32_e32 v69, 0x45800000, v68
	v_cndmask_b32_e32 v68, v68, v69, vcc
	v_pk_mul_f32 v[60:61], v[60:61], v[68:69] op_sel_hi:[1,0]
	v_pk_mul_f32 v[62:63], v[62:63], v[68:69] op_sel_hi:[1,0]
	v_pk_mul_f32 v[56:57], v[56:57], v[68:69] op_sel_hi:[1,0]
	v_pk_mul_f32 v[58:59], v[58:59], v[68:69] op_sel_hi:[1,0]
	v_pk_mul_f32 v[70:71], v[52:53], v[68:69] op_sel_hi:[1,0]
	v_pk_mul_f32 v[72:73], v[54:55], v[68:69] op_sel_hi:[1,0]
	v_pk_mul_f32 v[74:75], v[48:49], v[68:69] op_sel_hi:[1,0]
	v_pk_mul_f32 v[68:69], v[50:51], v[68:69] op_sel_hi:[1,0]
	v_pk_mul_f32 v[50:51], v[14:15], v[62:63]
	v_pk_mul_f32 v[48:49], v[12:13], v[60:61]
	v_pk_mul_f32 v[54:55], v[10:11], v[58:59]
	v_pk_mul_f32 v[52:53], v[8:9], v[56:57]
	v_pk_mul_f32 v[58:59], v[6:7], v[72:73]
	v_pk_mul_f32 v[56:57], v[4:5], v[70:71]
	v_pk_mul_f32 v[62:63], v[2:3], v[68:69]
	v_pk_mul_f32 v[60:61], v[0:1], v[74:75]
	global_store_dwordx4 v[64:65], v[48:51], off
	global_store_dwordx4 v[64:65], v[52:55], off offset:64
	global_store_dwordx4 v[64:65], v[56:59], off offset:512
	global_store_dwordx4 v[64:65], v[60:63], off offset:576
	global_load_dwordx4 v[48:51], v[66:67], off
	s_nop 0
	global_load_dwordx4 v[52:55], v[66:67], off offset:16
	global_load_dwordx4 v[56:59], v[66:67], off offset:32
	global_load_dwordx4 v[60:63], v[66:67], off offset:48
	s_waitcnt vmcnt(2)
	v_pk_add_f32 v[50:51], v[50:51], v[54:55]
	v_pk_add_f32 v[48:49], v[48:49], v[52:53]
	s_waitcnt vmcnt(0)
	v_pk_add_f32 v[52:53], v[58:59], v[62:63]
	v_pk_add_f32 v[54:55], v[56:57], v[60:61]
	v_pk_add_f32 v[50:51], v[50:51], v[52:53]
	v_pk_add_f32 v[48:49], v[48:49], v[54:55]
	s_nop 0
	v_pk_mov_b32 v[52:53], v[48:49], v[50:51] op_sel:[1,0]
	v_mov_b32_e32 v49, v51
	v_pk_add_f32 v[48:49], v[52:53], v[48:49]
	v_lshl_add_u64 v[50:51], s[0:1], 0, v[186:187]
	v_add_f32_e32 v48, v48, v49
	v_fmamk_f32 v48, v48, 0x3a800000, v134
	v_mul_f32_e32 v49, 0x4b800000, v48
	v_cmp_gt_f32_e32 vcc, s2, v48
	s_nop 1
	v_cndmask_b32_e32 v48, v48, v49, vcc
	v_rsq_f32_e32 v52, v48
	v_lshl_add_u64 v[48:49], s[76:77], 0, v[156:157]
	v_lshl_add_u64 v[48:49], v[48:49], 0, v[144:145]
	v_mul_f32_e32 v53, 0x45800000, v52
	v_cndmask_b32_e32 v52, v52, v53, vcc
	v_pk_mul_f32 v[44:45], v[44:45], v[52:53] op_sel_hi:[1,0]
	v_pk_mul_f32 v[46:47], v[46:47], v[52:53] op_sel_hi:[1,0]
	v_pk_mul_f32 v[40:41], v[40:41], v[52:53] op_sel_hi:[1,0]
	v_pk_mul_f32 v[42:43], v[42:43], v[52:53] op_sel_hi:[1,0]
	v_pk_mul_f32 v[54:55], v[36:37], v[52:53] op_sel_hi:[1,0]
	v_pk_mul_f32 v[56:57], v[38:39], v[52:53] op_sel_hi:[1,0]
	v_pk_mul_f32 v[58:59], v[32:33], v[52:53] op_sel_hi:[1,0]
	v_pk_mul_f32 v[52:53], v[34:35], v[52:53] op_sel_hi:[1,0]
	v_pk_mul_f32 v[34:35], v[14:15], v[46:47]
	v_pk_mul_f32 v[32:33], v[12:13], v[44:45]
	v_pk_mul_f32 v[38:39], v[10:11], v[42:43]
	v_pk_mul_f32 v[36:37], v[8:9], v[40:41]
	v_pk_mul_f32 v[42:43], v[6:7], v[56:57]
	v_pk_mul_f32 v[40:41], v[4:5], v[54:55]
	v_pk_mul_f32 v[46:47], v[2:3], v[52:53]
	v_pk_mul_f32 v[44:45], v[0:1], v[58:59]
	global_store_dwordx4 v[48:49], v[32:35], off
	global_store_dwordx4 v[48:49], v[36:39], off offset:64
	global_store_dwordx4 v[48:49], v[40:43], off offset:512
	global_store_dwordx4 v[48:49], v[44:47], off offset:576
	global_load_dwordx4 v[32:35], v[50:51], off
	s_nop 0
	global_load_dwordx4 v[36:39], v[50:51], off offset:16
	global_load_dwordx4 v[40:43], v[50:51], off offset:32
	global_load_dwordx4 v[44:47], v[50:51], off offset:48
	s_waitcnt vmcnt(2)
	v_pk_add_f32 v[34:35], v[34:35], v[38:39]
	v_pk_add_f32 v[32:33], v[32:33], v[36:37]
	s_waitcnt vmcnt(0)
	v_pk_add_f32 v[36:37], v[42:43], v[46:47]
	v_pk_add_f32 v[38:39], v[40:41], v[44:45]
	v_pk_add_f32 v[34:35], v[34:35], v[36:37]
	v_pk_add_f32 v[32:33], v[32:33], v[38:39]
	v_lshl_add_u64 v[44:45], s[0:1], 0, v[132:133]
	v_pk_mov_b32 v[36:37], v[32:33], v[34:35] op_sel:[1,0]
	v_mov_b32_e32 v33, v35
	v_pk_add_f32 v[32:33], v[36:37], v[32:33]
	s_movk_i32 s0, 0x80
	v_add_f32_e32 v32, v32, v33
	v_fmamk_f32 v32, v32, 0x3a800000, v134
	v_mul_f32_e32 v33, 0x4b800000, v32
	v_cmp_gt_f32_e32 vcc, s2, v32
	s_nop 1
	v_cndmask_b32_e32 v32, v32, v33, vcc
	v_rsq_f32_e32 v34, v32
	v_lshl_add_u64 v[32:33], s[76:77], 0, v[158:159]
	v_lshl_add_u64 v[46:47], v[32:33], 0, v[144:145]
	v_mul_f32_e32 v32, 0x45800000, v34
	v_cndmask_b32_e32 v32, v34, v32, vcc
	v_pk_mul_f32 v[34:35], v[166:167], v[32:33] op_sel_hi:[1,0]
	v_pk_mul_f32 v[36:37], v[160:161], v[32:33] op_sel_hi:[1,0]
	v_pk_mul_f32 v[38:39], v[164:165], v[32:33] op_sel_hi:[1,0]
	v_pk_mul_f32 v[40:41], v[30:31], v[32:33] op_sel_hi:[1,0]
	v_pk_mul_f32 v[42:43], v[162:163], v[32:33] op_sel_hi:[1,0]
	v_pk_mul_f32 v[48:49], v[28:29], v[32:33] op_sel_hi:[1,0]
	v_pk_mul_f32 v[50:51], v[170:171], v[32:33] op_sel_hi:[1,0]
	v_pk_mul_f32 v[52:53], v[168:169], v[32:33] op_sel_hi:[1,0]
	v_pk_mul_f32 v[30:31], v[14:15], v[36:37]
	v_pk_mul_f32 v[28:29], v[12:13], v[34:35]
	v_pk_mul_f32 v[34:35], v[10:11], v[40:41]
	v_pk_mul_f32 v[32:33], v[8:9], v[38:39]
	v_pk_mul_f32 v[38:39], v[6:7], v[48:49]
	v_pk_mul_f32 v[36:37], v[4:5], v[42:43]
	v_pk_mul_f32 v[42:43], v[2:3], v[52:53]
	v_pk_mul_f32 v[40:41], v[0:1], v[50:51]
	global_store_dwordx4 v[46:47], v[28:31], off
	global_store_dwordx4 v[46:47], v[32:35], off offset:64
	global_store_dwordx4 v[46:47], v[36:39], off offset:512
	global_store_dwordx4 v[46:47], v[40:43], off offset:576
	global_load_dwordx4 v[28:31], v[44:45], off
	s_nop 0
	global_load_dwordx4 v[32:35], v[44:45], off offset:16
	global_load_dwordx4 v[36:39], v[44:45], off offset:32
	global_load_dwordx4 v[40:43], v[44:45], off offset:48
	v_lshl_add_u64 v[44:45], s[76:77], 0, v[172:173]
	s_waitcnt vmcnt(2)
	v_pk_add_f32 v[30:31], v[30:31], v[34:35]
	v_pk_add_f32 v[28:29], v[28:29], v[32:33]
	s_waitcnt vmcnt(0)
	v_pk_add_f32 v[32:33], v[38:39], v[42:43]
	v_pk_add_f32 v[34:35], v[36:37], v[40:41]
	v_pk_add_f32 v[30:31], v[30:31], v[32:33]
	v_pk_add_f32 v[28:29], v[28:29], v[34:35]
	s_nop 0
	v_pk_mov_b32 v[32:33], v[28:29], v[30:31] op_sel:[1,0]
	v_mov_b32_e32 v29, v31
	v_pk_add_f32 v[28:29], v[32:33], v[28:29]
	v_lshl_add_u64 v[30:31], v[44:45], 0, v[144:145]
	v_add_f32_e32 v28, v28, v29
	v_fmamk_f32 v28, v28, 0x3a800000, v134
	v_mul_f32_e32 v29, 0x4b800000, v28
	v_cmp_gt_f32_e32 vcc, s2, v28
	s_nop 1
	v_cndmask_b32_e32 v28, v28, v29, vcc
	v_rsq_f32_e32 v29, v28
	v_lshl_add_u32 v28, s92, 3, v190
	v_mul_f32_e32 v32, 0x45800000, v29
	v_cndmask_b32_e32 v32, v29, v32, vcc
	v_pk_mul_f32 v[26:27], v[26:27], v[32:33] op_sel_hi:[1,0]
	v_pk_mul_f32 v[20:21], v[20:21], v[32:33] op_sel_hi:[1,0]
	v_pk_mul_f32 v[24:25], v[24:25], v[32:33] op_sel_hi:[1,0]
	v_pk_mul_f32 v[18:19], v[18:19], v[32:33] op_sel_hi:[1,0]
	v_pk_mul_f32 v[22:23], v[22:23], v[32:33] op_sel_hi:[1,0]
	v_pk_mul_f32 v[16:17], v[16:17], v[32:33] op_sel_hi:[1,0]
	v_pk_mul_f32 v[34:35], v[130:131], v[32:33] op_sel_hi:[1,0]
	v_pk_mul_f32 v[32:33], v[128:129], v[32:33] op_sel_hi:[1,0]
	v_pk_mul_f32 v[14:15], v[14:15], v[20:21]
	v_pk_mul_f32 v[12:13], v[12:13], v[26:27]
	v_cmp_gt_i32_e32 vcc, s0, v28
	v_pk_mul_f32 v[10:11], v[10:11], v[18:19]
	v_pk_mul_f32 v[8:9], v[8:9], v[24:25]
	v_pk_mul_f32 v[6:7], v[6:7], v[16:17]
	v_pk_mul_f32 v[4:5], v[4:5], v[22:23]
	v_pk_mul_f32 v[2:3], v[2:3], v[32:33]
	v_pk_mul_f32 v[0:1], v[0:1], v[34:35]
	global_store_dwordx4 v[30:31], v[12:15], off
	global_store_dwordx4 v[30:31], v[8:11], off offset:64
	global_store_dwordx4 v[30:31], v[4:7], off offset:512
	global_store_dwordx4 v[30:31], v[0:3], off offset:576
	s_and_saveexec_b64 s[0:1], vcc
	s_cbranch_execz .LBB0_974
	v_ashrrev_i32_e32 v29, 31, v28
	v_lshlrev_b64 v[20:21], 12, v[28:29]
	v_lshlrev_b32_e32 v22, 4, v191
	v_mov_b32_e32 v23, 0
	v_lshl_add_u64 v[20:21], s[76:77], 0, v[20:21]
	v_lshl_add_u64 v[20:21], v[20:21], 0, v[22:23]
	s_brev_b32 s0, 32
	v_mov_b32_e32 v0, v216
	v_mov_b32_e32 v1, v217
	v_mov_b32_e32 v2, v218
	v_mov_b32_e32 v3, v219
	v_mov_b32_e32 v4, v220
	v_mov_b32_e32 v5, v221
	v_mov_b32_e32 v6, v222
	v_mov_b32_e32 v7, v223
	v_mov_b32_e32 v8, v224
	v_mov_b32_e32 v9, v225
	v_mov_b32_e32 v10, v226
	v_mov_b32_e32 v11, v227
	v_mov_b32_e32 v12, v228
	v_mov_b32_e32 v13, v229
	v_mov_b32_e32 v14, v230
	v_mov_b32_e32 v15, v231
	v_mov_b32_e32 v16, v236
	v_mov_b32_e32 v17, v237
	v_mov_b32_e32 v18, v238
	v_mov_b32_e32 v19, v239
	v_pk_mul_f32 v[24:25], v[2:3], v[2:3]
	v_pk_mul_f32 v[26:27], v[0:1], v[0:1]
	v_mul_f32_e32 v28, v5, v5
	v_mul_f32_e32 v30, v7, v7
	v_pk_mul_f32 v[32:33], v[10:11], v[10:11]
	v_pk_mul_f32 v[34:35], v[8:9], v[8:9]
	v_pk_mov_b32 v[36:37], v[26:27], v[24:25] op_sel:[1,0]
	v_mov_b32_e32 v27, v25
	v_mul_f32_e32 v40, v14, v14
	v_mul_f32_e32 v41, v15, v15
	v_pk_fma_f32 v[24:25], v[4:5], v[4:5], v[28:29] op_sel_hi:[1,1,0]
	v_pk_fma_f32 v[28:29], v[6:7], v[6:7], v[30:31] op_sel_hi:[1,1,0]
	v_pk_mov_b32 v[30:31], v[34:35], v[32:33] op_sel:[1,0]
	v_mov_b32_e32 v35, v33
	v_pk_add_f32 v[26:27], v[36:37], v[26:27]
	v_mov_b32_e32 v25, v40
	v_mov_b32_e32 v29, v41
	v_pk_add_f32 v[30:31], v[30:31], v[34:35]
	v_mul_f32_e32 v38, v12, v12
	v_mul_f32_e32 v39, v13, v13
	v_pk_add_f32 v[26:27], v[26:27], v[26:27] op_sel:[0,1] op_sel_hi:[1,0]
	v_pk_add_f32 v[24:25], v[24:25], v[28:29]
	v_pk_add_f32 v[28:29], v[30:31], v[30:31] op_sel:[0,1] op_sel_hi:[1,0]
	v_mov_b32_e32 v27, v39
	v_mov_b32_e32 v29, v38
	v_pk_add_f32 v[26:27], v[28:29], v[26:27]
	s_nop 0
	v_pk_add_f32 v[24:25], v[26:27], v[24:25]
	s_nop 0
	v_add_f32_e32 v24, v24, v25
	s_nop 1
	v_add_f32_dpp v24, v24, v24 quad_perm:[1,0,3,2] row_mask:0xf bank_mask:0xf
	s_nop 1
	v_add_f32_dpp v24, v24, v24 quad_perm:[2,3,0,1] row_mask:0xf bank_mask:0xf
	s_nop 1
	v_add_f32_dpp v24, v24, v24 row_half_mirror row_mask:0xf bank_mask:0xf
	s_nop 1
	v_add_f32_dpp v24, v24, v24 row_mirror row_mask:0xf bank_mask:0xf
	v_mov_b32_e32 v25, v24
	s_nop 1
	v_permlane16_swap_b32_e32 v25, v24
	s_nop 0
	v_add_f32_e32 v24, v24, v25
	v_mov_b32_e32 v25, v24
	s_nop 1
	v_permlane32_swap_b32_e32 v25, v24
	s_nop 0
	s_waitcnt lgkmcnt(0)
	v_add_f32_e32 v23, v24, v25
	v_fmac_f32_e32 v134, 0x3a800000, v23
	v_mul_f32_e32 v23, 0x4b800000, v134
	v_cmp_gt_f32_e32 vcc, s2, v134
	v_add_co_u32_e64 v24, s[0:1], s0, v20
	s_nop 0
	v_cndmask_b32_e32 v23, v134, v23, vcc
	v_rsq_f32_e32 v23, v23
	v_addc_co_u32_e64 v25, s[0:1], 0, v21, s[0:1]
	s_mov_b64 s[0:1], 0x4000000
	v_mul_f32_e32 v26, 0x45800000, v23
	v_cndmask_b32_e32 v26, v23, v26, vcc
	v_pk_mul_f32 v[8:9], v[8:9], v[26:27] op_sel_hi:[1,0]
	v_pk_mul_f32 v[10:11], v[10:11], v[26:27] op_sel_hi:[1,0]
	v_pk_mul_f32 v[8:9], v[16:17], v[8:9]
	v_pk_mul_f32 v[10:11], v[18:19], v[10:11]
	global_store_dwordx4 v[24:25], v[8:11], off
	v_pk_mul_f32 v[2:3], v[2:3], v[26:27] op_sel_hi:[1,0]
	v_pk_mul_f32 v[0:1], v[0:1], v[26:27] op_sel_hi:[1,0]
	v_lshl_add_u64 v[16:17], v[20:21], 0, s[0:1]
	v_pk_mul_f32 v[6:7], v[6:7], v[26:27] op_sel_hi:[1,0]
	v_pk_mul_f32 v[4:5], v[4:5], v[26:27] op_sel_hi:[1,0]
	v_pk_mul_f32 v[0:1], v[240:241], v[0:1]
	v_pk_mul_f32 v[2:3], v[242:243], v[2:3]
	global_store_dwordx4 v[16:17], v[0:3], off offset:1024
	v_pk_mul_f32 v[32:33], v[244:245], v[4:5]
	v_pk_mul_f32 v[34:35], v[246:247], v[6:7]
	global_store_dwordx4 v[16:17], v[32:35], off offset:2048
	v_pk_mul_f32 v[4:5], v[14:15], v[26:27] op_sel_hi:[1,0]
	v_pk_mul_f32 v[6:7], v[12:13], v[26:27] op_sel_hi:[1,0]
	v_pk_mul_f32 v[38:39], v[250:251], v[4:5]
	v_pk_mul_f32 v[36:37], v[248:249], v[6:7]
	global_store_dwordx4 v[16:17], v[36:39], off offset:3072
